# phase F2: gain vector fetched in one batch instead of four waited 2-load pieces (store-ack waits dropped)
# baseline (speedup 1.0000x reference)
.LBB0_98:
	v_ashrrev_i32_e32 v16, 4, v79
	v_ashrrev_i32_e32 v17, 31, v16
	v_lshlrev_b64 v[0:1], 11, v[16:17]
	v_lshl_add_u64 v[0:1], v[8:9], 0, v[0:1]
	global_load_dwordx4 v[12:15], v[0:1], off offset:48
	global_load_dwordx4 v[40:43], v[0:1], off offset:32
	global_load_dwordx4 v[26:29], v[0:1], off offset:16
	global_load_dwordx4 v[18:21], v[0:1], off
	global_load_dwordx4 v[80:83], v[0:1], off offset:1072
	global_load_dwordx4 v[60:63], v[0:1], off offset:1056
	global_load_dwordx4 v[44:47], v[0:1], off offset:1040
	global_load_dwordx4 v[30:33], v[0:1], off offset:1024
	v_mov_b32_e32 v11, v129
	s_add_i32 s0, s0, s1
	v_add_u32_e32 v79, s26, v79
	s_cmpk_gt_i32 s0, 0x13f
	s_waitcnt vmcnt(0)
	v_lshlrev_b32_e32 v50, 16, v12
	v_lshlrev_b32_e32 v48, 16, v42
	v_lshlrev_b32_e32 v34, 16, v28
	v_lshlrev_b32_e32 v68, 16, v20
	v_and_b32_e32 v69, 0xffff0000, v20
	v_lshlrev_b32_e32 v70, 16, v21
	v_and_b32_e32 v71, 0xffff0000, v21
	v_lshlrev_b32_e32 v72, 16, v32
	v_and_b32_e32 v73, 0xffff0000, v32
	v_lshlrev_b32_e32 v74, 16, v33
	v_and_b32_e32 v75, 0xffff0000, v33
	v_lshlrev_b32_e32 v38, 16, v46
	v_and_b32_e32 v39, 0xffff0000, v46
	v_lshlrev_b32_e32 v56, 16, v47
	v_and_b32_e32 v57, 0xffff0000, v47
	v_lshlrev_b32_e32 v46, 16, v60
	v_and_b32_e32 v47, 0xffff0000, v60
	v_lshlrev_b32_e32 v52, 16, v61
	v_and_b32_e32 v53, 0xffff0000, v61
	v_lshlrev_b32_e32 v60, 16, v62
	v_and_b32_e32 v61, 0xffff0000, v62
	v_lshlrev_b32_e32 v64, 16, v63
	v_and_b32_e32 v65, 0xffff0000, v63
	v_lshlrev_b32_e32 v62, 16, v80
	v_and_b32_e32 v63, 0xffff0000, v80
	v_lshlrev_b32_e32 v66, 16, v81
	v_and_b32_e32 v67, 0xffff0000, v81
	v_pk_fma_f32 v[80:81], v[4:5], v[74:75], v[70:71] neg_lo:[1,0,0] neg_hi:[1,0,0]
	v_pk_fma_f32 v[84:85], v[4:5], v[72:73], v[68:69] neg_lo:[1,0,0] neg_hi:[1,0,0]
	global_load_dwordx4 v[68:71], v[6:7], off offset:16
	global_load_dwordx4 v[72:75], v[6:7], off
	global_load_dwordx4 v[100:103], v[6:7], off offset:48
	global_load_dwordx4 v[104:107], v[6:7], off offset:32
	global_load_dwordx4 v[108:111], v[6:7], off offset:80
	global_load_dwordx4 v[112:115], v[6:7], off offset:64
	global_load_dwordx4 v[116:119], v[6:7], off offset:112
	global_load_dwordx4 v[120:123], v[6:7], off offset:96
	v_lshlrev_b32_e32 v20, 16, v30
	v_and_b32_e32 v21, 0xffff0000, v30
	v_lshlrev_b32_e32 v24, 16, v31
	v_and_b32_e32 v25, 0xffff0000, v31
	v_and_b32_e32 v35, 0xffff0000, v28
	v_lshlrev_b32_e32 v32, 16, v29
	v_and_b32_e32 v33, 0xffff0000, v29
	v_lshlrev_b32_e32 v28, 16, v44
	v_and_b32_e32 v29, 0xffff0000, v44
	v_lshlrev_b32_e32 v36, 16, v45
	v_and_b32_e32 v37, 0xffff0000, v45
	v_lshlrev_b32_e32 v30, 16, v40
	v_and_b32_e32 v31, 0xffff0000, v40
	v_lshlrev_b32_e32 v44, 16, v41
	v_and_b32_e32 v45, 0xffff0000, v41
	v_and_b32_e32 v49, 0xffff0000, v42
	v_lshlrev_b32_e32 v54, 16, v43
	v_and_b32_e32 v55, 0xffff0000, v43
	v_and_b32_e32 v51, 0xffff0000, v12
	v_lshlrev_b32_e32 v58, 16, v13
	v_and_b32_e32 v59, 0xffff0000, v13
	v_lshlrev_b32_e32 v13, 16, v14
	v_and_b32_e32 v12, 0xffff0000, v14
	v_lshlrev_b32_e32 v41, 16, v15
	v_and_b32_e32 v40, 0xffff0000, v15
	v_lshlrev_b32_e32 v15, 16, v82
	v_and_b32_e32 v14, 0xffff0000, v82
	v_lshlrev_b32_e32 v43, 16, v83
	v_and_b32_e32 v42, 0xffff0000, v83
	v_lshlrev_b32_e32 v0, 16, v18
	v_and_b32_e32 v1, 0xffff0000, v18
	v_pk_fma_f32 v[12:13], v[4:5], v[14:15], v[12:13] neg_lo:[1,0,0] neg_hi:[1,0,0]
	v_pk_fma_f32 v[14:15], v[4:5], v[42:43], v[40:41] neg_lo:[1,0,0] neg_hi:[1,0,0]
	v_mov_b64_e32 v[40:41], s[82:83]
	v_lshlrev_b32_e32 v2, 16, v19
	v_and_b32_e32 v3, 0xffff0000, v19
	v_mad_i64_i32 v[16:17], s[24:25], v16, s27, v[40:41]
	v_pk_fma_f32 v[0:1], v[4:5], v[20:21], v[0:1] neg_lo:[1,0,0] neg_hi:[1,0,0]
	v_lshl_add_u64 v[16:17], v[16:17], 0, v[128:129]
	v_pk_fma_f32 v[2:3], v[4:5], v[24:25], v[2:3] neg_lo:[1,0,0] neg_hi:[1,0,0]
	v_pk_mul_f32 v[90:91], v[0:1], v[0:1]
	v_lshl_add_u64 v[40:41], v[16:17], 0, v[10:11]
	v_pk_mul_f32 v[88:89], v[2:3], v[2:3]
	v_add_f32_e32 v11, v90, v91
	v_add_f32_e32 v11, v11, v88
	v_pk_mul_f32 v[86:87], v[84:85], v[84:85]
	v_add_f32_e32 v11, v89, v11
	v_add_f32_e32 v11, v86, v11
	v_lshlrev_b32_e32 v18, 16, v26
	v_and_b32_e32 v19, 0xffff0000, v26
	v_pk_mul_f32 v[82:83], v[80:81], v[80:81]
	v_add_f32_e32 v11, v87, v11
	v_pk_fma_f32 v[34:35], v[4:5], v[38:39], v[34:35] neg_lo:[1,0,0] neg_hi:[1,0,0]
	v_pk_fma_f32 v[38:39], v[4:5], v[28:29], v[18:19] neg_lo:[1,0,0] neg_hi:[1,0,0]
	v_add_f32_e32 v11, v82, v11
	v_lshlrev_b32_e32 v22, 16, v27
	v_and_b32_e32 v23, 0xffff0000, v27
	v_pk_mul_f32 v[96:97], v[38:39], v[38:39]
	v_add_f32_e32 v11, v83, v11
	v_pk_fma_f32 v[36:37], v[4:5], v[36:37], v[22:23] neg_lo:[1,0,0] neg_hi:[1,0,0]
	v_add_f32_e32 v11, v11, v96
	v_pk_mul_f32 v[94:95], v[36:37], v[36:37]
	v_add_f32_e32 v11, v97, v11
	v_add_f32_e32 v11, v94, v11
	v_pk_mul_f32 v[92:93], v[34:35], v[34:35]
	v_add_f32_e32 v11, v95, v11
	v_pk_fma_f32 v[32:33], v[4:5], v[56:57], v[32:33] neg_lo:[1,0,0] neg_hi:[1,0,0]
	v_add_f32_e32 v11, v92, v11
	v_pk_mul_f32 v[56:57], v[32:33], v[32:33]
	v_add_f32_e32 v11, v93, v11
	v_pk_fma_f32 v[30:31], v[4:5], v[46:47], v[30:31] neg_lo:[1,0,0] neg_hi:[1,0,0]
	v_add_f32_e32 v11, v56, v11
	v_pk_mul_f32 v[46:47], v[30:31], v[30:31]
	v_add_f32_e32 v11, v57, v11
	v_pk_fma_f32 v[28:29], v[4:5], v[52:53], v[44:45] neg_lo:[1,0,0] neg_hi:[1,0,0]
	v_add_f32_e32 v11, v11, v46
	v_pk_mul_f32 v[44:45], v[28:29], v[28:29]
	v_add_f32_e32 v11, v47, v11
	v_pk_fma_f32 v[24:25], v[4:5], v[60:61], v[48:49] neg_lo:[1,0,0] neg_hi:[1,0,0]
	v_add_f32_e32 v11, v44, v11
	v_pk_mul_f32 v[48:49], v[24:25], v[24:25]
	v_add_f32_e32 v11, v45, v11
	v_pk_fma_f32 v[22:23], v[4:5], v[64:65], v[54:55] neg_lo:[1,0,0] neg_hi:[1,0,0]
	v_add_f32_e32 v11, v48, v11
	v_pk_mul_f32 v[54:55], v[22:23], v[22:23]
	v_add_f32_e32 v11, v49, v11
	v_pk_fma_f32 v[20:21], v[4:5], v[62:63], v[50:51] neg_lo:[1,0,0] neg_hi:[1,0,0]
	v_add_f32_e32 v11, v54, v11
	v_pk_mul_f32 v[50:51], v[20:21], v[20:21]
	v_add_f32_e32 v11, v55, v11
	v_pk_fma_f32 v[18:19], v[4:5], v[66:67], v[58:59] neg_lo:[1,0,0] neg_hi:[1,0,0]
	v_add_f32_e32 v11, v11, v50
	v_pk_mul_f32 v[52:53], v[18:19], v[18:19]
	v_add_f32_e32 v11, v51, v11
	v_add_f32_e32 v11, v52, v11
	v_pk_mul_f32 v[26:27], v[12:13], v[12:13]
	v_add_f32_e32 v11, v53, v11
	v_add_f32_e32 v11, v27, v11
	v_pk_mul_f32 v[42:43], v[14:15], v[14:15]
	v_add_f32_e32 v11, v26, v11
	v_add_f32_e32 v11, v43, v11
	v_add_f32_e32 v11, v42, v11
	ds_bpermute_b32 v26, v77, v11
	s_mov_b64 s[24:25], 0xc65c800
	v_lshl_add_u64 v[16:17], v[40:41], 0, s[24:25]
	s_waitcnt lgkmcnt(0)
	v_add_f32_e32 v11, v11, v26
	ds_bpermute_b32 v26, v78, v11
	s_waitcnt lgkmcnt(0)
	v_add_f32_e32 v11, v11, v26
	v_fmamk_f32 v11, v11, 0x3c000000, v209
	v_cmp_gt_f32_e32 vcc, s3, v11
	v_mul_f32_e32 v26, 0x4b800000, v11
	s_nop 0
	v_cndmask_b32_e32 v11, v11, v26, vcc
	v_rsq_f32_e32 v11, v11
	s_nop 0
	v_mul_f32_e32 v26, 0x45800000, v11
	v_cndmask_b32_e32 v11, v11, v26, vcc
	v_mul_f32_e32 v26, v76, v11
	v_pk_mul_f32 v[0:1], v[0:1], v[26:27] op_sel_hi:[1,0]
	v_pk_mul_f32 v[2:3], v[2:3], v[26:27] op_sel_hi:[1,0]
	v_pk_mul_f32 v[42:43], v[84:85], v[26:27] op_sel_hi:[1,0]
	v_pk_mul_f32 v[44:45], v[80:81], v[26:27] op_sel_hi:[1,0]
	s_waitcnt vmcnt(0)
	v_pk_mul_f32 v[0:1], v[72:73], v[0:1]
	v_pk_mul_f32 v[2:3], v[74:75], v[2:3]
	v_pk_mul_f32 v[42:43], v[68:69], v[42:43]
	v_pk_mul_f32 v[44:45], v[70:71], v[44:45]
	v_add_co_u32_e32 v40, vcc, s28, v40
	v_cvt_pk_bf16_f32 v0, v0, v1
	v_cvt_pk_bf16_f32 v1, v2, v3
	v_cvt_pk_bf16_f32 v2, v42, v43
	v_cvt_pk_bf16_f32 v3, v44, v45
	v_addc_co_u32_e32 v41, vcc, 0, v41, vcc
	global_store_dwordx4 v[40:41], v[0:3], off offset:2048
	v_pk_mul_f32 v[42:43], v[38:39], v[26:27] op_sel_hi:[1,0]
	v_pk_mul_f32 v[34:35], v[34:35], v[26:27] op_sel_hi:[1,0]
	v_pk_mul_f32 v[36:37], v[36:37], v[26:27] op_sel_hi:[1,0]
	v_pk_mul_f32 v[24:25], v[24:25], v[26:27] op_sel_hi:[1,0]
	v_pk_mul_f32 v[28:29], v[28:29], v[26:27] op_sel_hi:[1,0]
	v_pk_mul_f32 v[12:13], v[12:13], v[26:27] op_sel_hi:[1,0]
	v_pk_mul_f32 v[18:19], v[18:19], v[26:27] op_sel_hi:[1,0]
	v_pk_mul_f32 v[34:35], v[100:101], v[34:35]
	v_pk_mul_f32 v[0:1], v[32:33], v[26:27] op_sel_hi:[1,0]
	v_pk_mul_f32 v[38:39], v[104:105], v[42:43]
	v_pk_mul_f32 v[36:37], v[106:107], v[36:37]
	v_pk_mul_f32 v[32:33], v[102:103], v[0:1]
	v_cvt_pk_bf16_f32 v0, v38, v39
	v_cvt_pk_bf16_f32 v1, v36, v37
	v_cvt_pk_bf16_f32 v2, v34, v35
	v_cvt_pk_bf16_f32 v3, v32, v33
	global_store_dwordx4 v[16:17], v[0:3], off offset:16
	v_pk_mul_f32 v[34:35], v[30:31], v[26:27] op_sel_hi:[1,0]
	v_pk_mul_f32 v[24:25], v[24:25], v[108:109]
	v_pk_mul_f32 v[0:1], v[22:23], v[26:27] op_sel_hi:[1,0]
	v_pk_mul_f32 v[30:31], v[34:35], v[112:113]
	v_pk_mul_f32 v[28:29], v[28:29], v[114:115]
	v_pk_mul_f32 v[22:23], v[0:1], v[110:111]
	v_cvt_pk_bf16_f32 v0, v30, v31
	v_cvt_pk_bf16_f32 v1, v28, v29
	v_cvt_pk_bf16_f32 v2, v24, v25
	v_cvt_pk_bf16_f32 v3, v22, v23
	global_store_dwordx4 v[16:17], v[0:3], off offset:32
	v_pk_mul_f32 v[24:25], v[20:21], v[26:27] op_sel_hi:[1,0]
	v_pk_mul_f32 v[12:13], v[12:13], v[116:117] op_sel:[1,0] op_sel_hi:[0,1]
	v_pk_mul_f32 v[0:1], v[14:15], v[26:27] op_sel_hi:[1,0]
	v_pk_mul_f32 v[20:21], v[24:25], v[120:121]
	v_pk_mul_f32 v[18:19], v[18:19], v[122:123]
	v_pk_mul_f32 v[14:15], v[0:1], v[118:119] op_sel:[1,0] op_sel_hi:[0,1]
	v_cvt_pk_bf16_f32 v0, v20, v21
	v_cvt_pk_bf16_f32 v1, v18, v19
	v_cvt_pk_bf16_f32 v2, v12, v13
	v_cvt_pk_bf16_f32 v3, v14, v15
	global_store_dwordx4 v[16:17], v[0:3], off offset:48
	s_cbranch_scc0 .LBB0_98
	s_movk_i32 s84, 0xc00
